# attention selection: rank indicators computed branch-free (v_cmp + s_and/s_or + v_cndmask) instead of exec-masked branches; on top of v19
# speedup vs baseline: 1.0157x; 1.0073x over previous
.LBB0_1716:
	s_andn2_b64 vcc, exec, s[10:11]
	s_cbranch_vccnz .LBB0_1970
	s_lshl_b32 s6, s3, 2
	v_or_b32_e32 v70, s6, v147
	v_lshl_add_u32 v71, v143, 2, s60
	v_lshl_add_u32 v72, v70, 2, 0
	v_lshl_add_u32 v68, v70, 7, v71
	v_add_u32_e32 v69, 0x1c000, v72
	v_add_u32_e32 v67, 0x1c400, v72
	v_add_u32_e32 v73, 0x1c480, v72
	v_add_u32_e32 v90, 0x1c500, v72
	v_add_u32_e32 v91, 0x1c580, v72
	v_add_u32_e32 v92, 0x1c600, v72
	v_add_u32_e32 v93, 0x1c680, v72
	v_add_u32_e32 v94, 0x1c700, v72
	v_add_u32_e32 v95, 0x1c780, v72
	ds_read2st64_b32 v[74:75], v68 offset1:16
	ds_read2_b32 v[76:77], v69 offset1:32
	ds_read2st64_b32 v[78:79], v68 offset0:32 offset1:48
	ds_read2_b32 v[80:81], v69 offset0:64 offset1:96
	ds_read2st64_b32 v[82:83], v68 offset0:64 offset1:80
	ds_read2_b32 v[84:85], v69 offset0:128 offset1:160
	ds_read2st64_b32 v[86:87], v68 offset0:96 offset1:112
	ds_read2_b32 v[88:89], v69 offset0:192 offset1:224
	ds_read_b32 v67, v67
	ds_read_b32 v73, v73
	ds_read_b32 v90, v90
	ds_read_b32 v91, v91
	ds_read_b32 v92, v92
	ds_read_b32 v93, v93
	ds_read_b32 v94, v94
	ds_read_b32 v95, v95
	v_cmp_eq_u32_e64 s[8:9], 16, v143
	v_cmp_eq_u32_e32 vcc, 0, v143
	s_waitcnt lgkmcnt(0)
	v_cndmask_b32_e64 v76, 0, v76, s[8:9]
	v_add_f32_e32 v74, v74, v76
	v_fma_f32 v67, v67, v74, 0
	v_cndmask_b32_e64 v74, 0, v77, s[8:9]
	v_add_f32_e32 v74, v75, v74
	v_fmac_f32_e32 v67, v73, v74
	v_cndmask_b32_e64 v73, 0, v80, s[8:9]
	v_add_f32_e32 v73, v78, v73
	v_fmac_f32_e32 v67, v90, v73
	v_cndmask_b32_e64 v73, 0, v81, s[8:9]
	v_add_f32_e32 v73, v79, v73
	v_fmac_f32_e32 v67, v91, v73
	v_cndmask_b32_e64 v73, 0, v84, s[8:9]
	v_add_f32_e32 v73, v82, v73
	v_fmac_f32_e32 v67, v92, v73
	v_cndmask_b32_e64 v73, 0, v85, s[8:9]
	v_add_f32_e32 v73, v83, v73
	s_add_i32 s6, s6, s54
	v_fmac_f32_e32 v67, v93, v73
	v_cndmask_b32_e64 v73, 0, v88, s[8:9]
	s_ashr_i32 s12, s6, 6
	v_add_f32_e32 v73, v86, v73
	v_cmp_eq_u32_e64 s[6:7], s12, v143
	v_fmac_f32_e32 v67, v94, v73
	v_cndmask_b32_e64 v73, 0, v89, s[8:9]
	s_or_b64 s[10:11], vcc, s[6:7]
	s_add_i32 s6, s12, -1
	v_add_f32_e32 v73, v87, v73
	v_cmp_eq_u32_e64 s[6:7], s6, v143
	v_fmac_f32_e32 v67, v95, v73
	s_or_b64 s[10:11], s[10:11], s[6:7]
	v_cmp_ge_i32_e64 s[6:7], s12, v143
	s_nop 1
	v_cndmask_b32_e64 v67, v187, v67, s[6:7]
	v_cndmask_b32_e64 v73, v67, v188, s[10:11]
	v_lshlrev_b32_e32 v67, 2, v194
	ds_bpermute_b32 v77, v67, v73
	ds_bpermute_b32 v76, v67, v73 offset:4
	ds_bpermute_b32 v79, v67, v73 offset:8
	ds_bpermute_b32 v78, v67, v73 offset:12
	ds_bpermute_b32 v81, v67, v73 offset:16
	ds_bpermute_b32 v80, v67, v73 offset:20
	ds_bpermute_b32 v83, v67, v73 offset:24
	ds_bpermute_b32 v82, v67, v73 offset:28
	ds_bpermute_b32 v85, v67, v73 offset:32
	ds_bpermute_b32 v84, v67, v73 offset:36
	ds_bpermute_b32 v87, v67, v73 offset:40
	ds_bpermute_b32 v86, v67, v73 offset:44
	ds_bpermute_b32 v89, v67, v73 offset:48
	ds_bpermute_b32 v88, v67, v73 offset:52
	ds_bpermute_b32 v91, v67, v73 offset:56
	ds_bpermute_b32 v90, v67, v73 offset:60
	s_waitcnt lgkmcnt(0)
	v_mov_b32_e32 v74, 1
	v_cmp_lt_f32_e64 s[12:13], v73, v77
	v_cmp_eq_f32_e64 s[18:19], v73, v77
	v_cmp_ne_u32_e64 s[36:37], 0, v143
	s_and_b64 s[18:19], s[18:19], s[36:37]
	s_or_b64 s[12:13], s[12:13], s[18:19]
	v_cndmask_b32_e64 v75, 0, 1, s[12:13]
	v_cmp_lt_f32_e64 s[12:13], v73, v76
	v_cmp_eq_f32_e64 s[18:19], v73, v76
	v_cmp_lt_u32_e64 s[36:37], 1, v143
	s_and_b64 s[18:19], s[18:19], s[36:37]
	s_or_b64 s[12:13], s[12:13], s[18:19]
	v_cndmask_b32_e64 v74, 0, 1, s[12:13]
	v_mov_b32_e32 v76, 1
	v_cmp_lt_f32_e64 s[12:13], v73, v79
	v_cmp_eq_f32_e64 s[18:19], v73, v79
	v_cmp_lt_u32_e64 s[36:37], 2, v143
	s_and_b64 s[18:19], s[18:19], s[36:37]
	s_or_b64 s[12:13], s[12:13], s[18:19]
	v_cndmask_b32_e64 v77, 0, 1, s[12:13]
	v_cmp_lt_f32_e64 s[12:13], v73, v78
	v_cmp_eq_f32_e64 s[18:19], v73, v78
	v_cmp_lt_u32_e64 s[36:37], 3, v143
	s_and_b64 s[18:19], s[18:19], s[36:37]
	s_or_b64 s[12:13], s[12:13], s[18:19]
	v_cndmask_b32_e64 v76, 0, 1, s[12:13]
	v_mov_b32_e32 v78, 1
	v_cmp_lt_f32_e64 s[12:13], v73, v81
	v_cmp_eq_f32_e64 s[18:19], v73, v81
	v_cmp_lt_u32_e64 s[36:37], 4, v143
	s_and_b64 s[18:19], s[18:19], s[36:37]
	s_or_b64 s[12:13], s[12:13], s[18:19]
	v_cndmask_b32_e64 v79, 0, 1, s[12:13]
	v_cmp_lt_f32_e64 s[12:13], v73, v80
	v_cmp_eq_f32_e64 s[18:19], v73, v80
	v_cmp_lt_u32_e64 s[36:37], 5, v143
	s_and_b64 s[18:19], s[18:19], s[36:37]
	s_or_b64 s[12:13], s[12:13], s[18:19]
	v_cndmask_b32_e64 v78, 0, 1, s[12:13]
	v_mov_b32_e32 v80, 1
	v_cmp_lt_f32_e64 s[12:13], v73, v83
	v_cmp_eq_f32_e64 s[18:19], v73, v83
	v_cmp_lt_u32_e64 s[36:37], 6, v143
	s_and_b64 s[18:19], s[18:19], s[36:37]
	s_or_b64 s[12:13], s[12:13], s[18:19]
	v_cndmask_b32_e64 v81, 0, 1, s[12:13]
	v_cmp_lt_f32_e64 s[12:13], v73, v82
	v_cmp_eq_f32_e64 s[18:19], v73, v82
	v_cmp_lt_u32_e64 s[36:37], 7, v143
	s_and_b64 s[18:19], s[18:19], s[36:37]
	s_or_b64 s[12:13], s[12:13], s[18:19]
	v_cndmask_b32_e64 v80, 0, 1, s[12:13]
	v_mov_b32_e32 v82, 1
	v_cmp_lt_f32_e64 s[12:13], v73, v85
	v_cmp_eq_f32_e64 s[18:19], v73, v85
	v_cmp_lt_u32_e64 s[36:37], 8, v143
	s_and_b64 s[18:19], s[18:19], s[36:37]
	s_or_b64 s[12:13], s[12:13], s[18:19]
	v_cndmask_b32_e64 v83, 0, 1, s[12:13]
	v_cmp_lt_f32_e64 s[12:13], v73, v84
	v_cmp_eq_f32_e64 s[18:19], v73, v84
	v_cmp_lt_u32_e64 s[36:37], 9, v143
	s_and_b64 s[18:19], s[18:19], s[36:37]
	s_or_b64 s[12:13], s[12:13], s[18:19]
	v_cndmask_b32_e64 v82, 0, 1, s[12:13]
	v_mov_b32_e32 v84, 1
	v_cmp_lt_f32_e64 s[12:13], v73, v87
	v_cmp_eq_f32_e64 s[18:19], v73, v87
	v_cmp_lt_u32_e64 s[36:37], 10, v143
	s_and_b64 s[18:19], s[18:19], s[36:37]
	s_or_b64 s[12:13], s[12:13], s[18:19]
	v_cndmask_b32_e64 v85, 0, 1, s[12:13]
	v_cmp_lt_f32_e64 s[12:13], v73, v86
	v_cmp_eq_f32_e64 s[18:19], v73, v86
	v_cmp_lt_u32_e64 s[36:37], 11, v143
	s_and_b64 s[18:19], s[18:19], s[36:37]
	s_or_b64 s[12:13], s[12:13], s[18:19]
	v_cndmask_b32_e64 v84, 0, 1, s[12:13]
	v_mov_b32_e32 v86, 1
	v_cmp_lt_f32_e64 s[12:13], v73, v89
	v_cmp_eq_f32_e64 s[18:19], v73, v89
	v_cmp_lt_u32_e64 s[36:37], 12, v143
	s_and_b64 s[18:19], s[18:19], s[36:37]
	s_or_b64 s[12:13], s[12:13], s[18:19]
	v_cndmask_b32_e64 v87, 0, 1, s[12:13]
	v_cmp_lt_f32_e64 s[12:13], v73, v88
	v_cmp_eq_f32_e64 s[18:19], v73, v88
	v_cmp_lt_u32_e64 s[36:37], 13, v143
	s_and_b64 s[18:19], s[18:19], s[36:37]
	s_or_b64 s[12:13], s[12:13], s[18:19]
	v_cndmask_b32_e64 v86, 0, 1, s[12:13]
	v_mov_b32_e32 v88, 1
	v_cmp_lt_f32_e64 s[12:13], v73, v91
	v_cmp_eq_f32_e64 s[18:19], v73, v91
	v_cmp_lt_u32_e64 s[36:37], 14, v143
	s_and_b64 s[18:19], s[18:19], s[36:37]
	s_or_b64 s[12:13], s[12:13], s[18:19]
	v_cndmask_b32_e64 v89, 0, 1, s[12:13]
	v_cmp_lt_f32_e64 s[12:13], v73, v90
	v_cmp_eq_f32_e64 s[18:19], v73, v90
	v_cmp_lt_u32_e64 s[36:37], 15, v143
	s_and_b64 s[18:19], s[18:19], s[36:37]
	s_or_b64 s[12:13], s[12:13], s[18:19]
	v_cndmask_b32_e64 v88, 0, 1, s[12:13]
	ds_bpermute_b32 v96, v67, v73 offset:64
	ds_bpermute_b32 v95, v67, v73 offset:68
	ds_bpermute_b32 v132, v67, v73 offset:72
	ds_bpermute_b32 v131, v67, v73 offset:76
	ds_bpermute_b32 v149, v67, v73 offset:80
	ds_bpermute_b32 v148, v67, v73 offset:84
	ds_bpermute_b32 v153, v67, v73 offset:88
	ds_bpermute_b32 v152, v67, v73 offset:92
	ds_bpermute_b32 v150, v67, v73 offset:96
	ds_bpermute_b32 v146, v67, v73 offset:100
	ds_bpermute_b32 v133, v67, v73 offset:104
	ds_bpermute_b32 v130, v67, v73 offset:108
	ds_bpermute_b32 v97, v67, v73 offset:112
	ds_bpermute_b32 v94, v67, v73 offset:116
	ds_bpermute_b32 v93, v67, v73 offset:120
	ds_bpermute_b32 v90, v67, v73 offset:124
	s_waitcnt lgkmcnt(0)
	v_mov_b32_e32 v91, 1
	v_cmp_lt_f32_e64 s[12:13], v73, v96
	v_cmp_eq_f32_e64 s[18:19], v73, v96
	v_cmp_lt_u32_e64 s[36:37], 16, v143
	s_and_b64 s[18:19], s[18:19], s[36:37]
	s_or_b64 s[12:13], s[12:13], s[18:19]
	v_cndmask_b32_e64 v92, 0, 1, s[12:13]
	v_cmp_lt_f32_e64 s[12:13], v73, v95
	v_cmp_eq_f32_e64 s[18:19], v73, v95
	v_cmp_lt_u32_e64 s[36:37], 17, v143
	s_and_b64 s[18:19], s[18:19], s[36:37]
	s_or_b64 s[12:13], s[12:13], s[18:19]
	v_cndmask_b32_e64 v91, 0, 1, s[12:13]
	v_mov_b32_e32 v95, 1
	v_cmp_lt_f32_e64 s[12:13], v73, v132
	v_cmp_eq_f32_e64 s[18:19], v73, v132
	v_cmp_lt_u32_e64 s[36:37], 18, v143
	s_and_b64 s[18:19], s[18:19], s[36:37]
	s_or_b64 s[12:13], s[12:13], s[18:19]
	v_cndmask_b32_e64 v96, 0, 1, s[12:13]
	v_cmp_lt_f32_e64 s[12:13], v73, v131
	v_cmp_eq_f32_e64 s[18:19], v73, v131
	v_cmp_lt_u32_e64 s[36:37], 19, v143
	s_and_b64 s[18:19], s[18:19], s[36:37]
	s_or_b64 s[12:13], s[12:13], s[18:19]
	v_cndmask_b32_e64 v95, 0, 1, s[12:13]
	v_mov_b32_e32 v131, 1
	v_cmp_lt_f32_e64 s[12:13], v73, v149
	v_cmp_eq_f32_e64 s[18:19], v73, v149
	v_cmp_lt_u32_e64 s[36:37], 20, v143
	s_and_b64 s[18:19], s[18:19], s[36:37]
	s_or_b64 s[12:13], s[12:13], s[18:19]
	v_cndmask_b32_e64 v132, 0, 1, s[12:13]
	v_cmp_lt_f32_e64 s[12:13], v73, v148
	v_cmp_eq_f32_e64 s[18:19], v73, v148
	v_cmp_lt_u32_e64 s[36:37], 21, v143
	s_and_b64 s[18:19], s[18:19], s[36:37]
	s_or_b64 s[12:13], s[12:13], s[18:19]
	v_cndmask_b32_e64 v131, 0, 1, s[12:13]
	v_mov_b32_e32 v148, 1
	v_cmp_lt_f32_e64 s[12:13], v73, v153
	v_cmp_eq_f32_e64 s[18:19], v73, v153
	v_cmp_lt_u32_e64 s[36:37], 22, v143
	s_and_b64 s[18:19], s[18:19], s[36:37]
	s_or_b64 s[12:13], s[12:13], s[18:19]
	v_cndmask_b32_e64 v149, 0, 1, s[12:13]
	v_cmp_lt_f32_e64 s[12:13], v73, v152
	v_cmp_eq_f32_e64 s[18:19], v73, v152
	v_cmp_lt_u32_e64 s[36:37], 23, v143
	s_and_b64 s[18:19], s[18:19], s[36:37]
	s_or_b64 s[12:13], s[12:13], s[18:19]
	v_cndmask_b32_e64 v148, 0, 1, s[12:13]
	v_mov_b32_e32 v152, 1
	v_cmp_lt_f32_e64 s[12:13], v73, v150
	v_cmp_eq_f32_e64 s[18:19], v73, v150
	v_cmp_lt_u32_e64 s[36:37], 24, v143
	s_and_b64 s[18:19], s[18:19], s[36:37]
	s_or_b64 s[12:13], s[12:13], s[18:19]
	v_cndmask_b32_e64 v153, 0, 1, s[12:13]
	v_cmp_lt_f32_e64 s[12:13], v73, v146
	v_cmp_eq_f32_e64 s[18:19], v73, v146
	v_cmp_lt_u32_e64 s[36:37], 25, v143
	s_and_b64 s[18:19], s[18:19], s[36:37]
	s_or_b64 s[12:13], s[12:13], s[18:19]
	v_cndmask_b32_e64 v152, 0, 1, s[12:13]
	v_mov_b32_e32 v146, 1
	v_cmp_lt_f32_e64 s[12:13], v73, v133
	v_cmp_eq_f32_e64 s[18:19], v73, v133
	v_cmp_lt_u32_e64 s[36:37], 26, v143
	s_and_b64 s[18:19], s[18:19], s[36:37]
	s_or_b64 s[12:13], s[12:13], s[18:19]
	v_cndmask_b32_e64 v150, 0, 1, s[12:13]
	v_cmp_lt_f32_e64 s[12:13], v73, v130
	v_cmp_eq_f32_e64 s[18:19], v73, v130
	v_cmp_lt_u32_e64 s[36:37], 27, v143
	s_and_b64 s[18:19], s[18:19], s[36:37]
	s_or_b64 s[12:13], s[12:13], s[18:19]
	v_cndmask_b32_e64 v146, 0, 1, s[12:13]
	v_mov_b32_e32 v130, 1
	v_cmp_lt_f32_e64 s[12:13], v73, v97
	v_cmp_eq_f32_e64 s[18:19], v73, v97
	v_cmp_lt_u32_e64 s[36:37], 28, v143
	s_and_b64 s[18:19], s[18:19], s[36:37]
	s_or_b64 s[12:13], s[12:13], s[18:19]
	v_cndmask_b32_e64 v133, 0, 1, s[12:13]
	v_cmp_lt_f32_e64 s[12:13], v73, v94
	v_cmp_eq_f32_e64 s[18:19], v73, v94
	v_cmp_lt_u32_e64 s[36:37], 29, v143
	s_and_b64 s[18:19], s[18:19], s[36:37]
	s_or_b64 s[12:13], s[12:13], s[18:19]
	v_cndmask_b32_e64 v130, 0, 1, s[12:13]
	v_cmp_lt_f32_e64 s[12:13], v73, v93
	v_cmp_eq_f32_e64 s[18:19], v73, v93
	v_cmp_eq_u32_e64 s[36:37], 31, v143
	s_and_b64 s[18:19], s[18:19], s[36:37]
	s_or_b64 s[12:13], s[12:13], s[18:19]
	v_cndmask_b32_e64 v94, 0, 1, s[12:13]
	v_add3_u32 v74, v74, v75, v77
	v_add3_u32 v74, v74, v76, v79
	v_add3_u32 v74, v74, v78, v81
	v_add3_u32 v74, v74, v80, v83
	v_add3_u32 v74, v74, v82, v85
	v_add3_u32 v74, v74, v84, v87
	v_add3_u32 v74, v74, v86, v89
	v_cmp_lt_f32_e64 s[12:13], v73, v90
	s_nop 1
	v_addc_co_u32_e64 v73, s[12:13], v74, v88, s[12:13]
	v_add_u32_e32 v73, v73, v92
	v_add3_u32 v73, v73, v91, v96
	v_add3_u32 v73, v73, v95, v132
	v_add3_u32 v73, v73, v131, v149
	v_add3_u32 v73, v73, v148, v153
	v_add3_u32 v73, v73, v152, v150
	v_add3_u32 v73, v73, v146, v133
	v_add3_u32 v73, v73, v130, v94
	v_cmp_gt_u32_e64 s[12:13], 16, v73
	s_and_b64 s[12:13], s[12:13], s[6:7]
	s_nop 0
	v_cndmask_b32_e64 v73, 0, 1, s[12:13]
	v_cmp_ne_u32_e64 s[12:13], 0, v73
	s_and_saveexec_b64 s[18:19], vcc
	s_nop 0
	v_mov_b32_e32 v73, s13
	v_mov_b32_e32 v74, s12
	v_add_u32_e32 v72, 0x24000, v72
	v_cndmask_b32_e64 v73, v73, v74, s[4:5]
	ds_write_b32 v72, v73
	s_or_b64 exec, exec, s[18:19]
	v_or_b32_e32 v70, 2, v70
	v_lshl_add_u32 v71, v70, 7, v71
	v_lshl_add_u32 v70, v70, 2, 0
	v_add_u32_e32 v95, 0x1c000, v70
	v_add_u32_e32 v96, 0x1c400, v70
	v_add_u32_e32 v97, 0x1c480, v70
	v_add_u32_e32 v130, 0x1c500, v70
	v_add_u32_e32 v131, 0x1c580, v70
	ds_read2st64_b32 v[72:73], v68 offset0:17 offset1:33
	ds_read2_b32 v[74:75], v69 offset0:34 offset1:66
	ds_read2st64_b32 v[76:77], v68 offset0:49 offset1:65
	ds_read2_b32 v[78:79], v69 offset0:98 offset1:130
	ds_read2st64_b32 v[80:81], v68 offset0:81 offset1:97
	ds_read2_b32 v[82:83], v69 offset0:162 offset1:194
	ds_read_b32 v71, v71
	ds_read_b32 v95, v95
	ds_read_b32 v96, v96
	ds_read_b32 v97, v97
	ds_read_b32 v130, v130
	ds_read_b32 v131, v131
	ds_read_b32 v68, v68 offset:28928
	ds_read_b32 v69, v69 offset:904
	v_add_u32_e32 v132, 0x1c600, v70
	v_add_u32_e32 v133, 0x1c680, v70
	v_add_u32_e32 v146, 0x1c700, v70
	v_add_u32_e32 v148, 0x1c780, v70
	ds_read_b32 v132, v132
	ds_read_b32 v133, v133
	ds_read_b32 v146, v146
	ds_read_b32 v148, v148
	v_or_b32_e32 v84, 4, v67
	v_or_b32_e32 v85, 8, v67
	v_or_b32_e32 v86, 12, v67
	v_or_b32_e32 v87, 16, v67
	v_or_b32_e32 v88, 20, v67
	v_or_b32_e32 v89, 24, v67
	v_or_b32_e32 v90, 28, v67
	v_or_b32_e32 v91, 32, v67
	v_or_b32_e32 v92, 36, v67
	v_or_b32_e32 v93, 40, v67
	v_or_b32_e32 v94, 44, v67
	v_or_b32_e32 v149, 48, v67
	v_or_b32_e32 v150, 52, v67
	v_or_b32_e32 v152, 56, v67
	v_or_b32_e32 v153, 60, v67
	s_waitcnt lgkmcnt(0)
	v_cndmask_b32_e64 v95, 0, v95, s[8:9]
	v_add_f32_e32 v71, v71, v95
	v_cndmask_b32_e64 v74, 0, v74, s[8:9]
	v_fma_f32 v71, v96, v71, 0
	v_add_f32_e32 v72, v72, v74
	v_fmac_f32_e32 v71, v97, v72
	v_cndmask_b32_e64 v72, 0, v75, s[8:9]
	v_add_f32_e32 v72, v73, v72
	v_fmac_f32_e32 v71, v130, v72
	v_cndmask_b32_e64 v72, 0, v78, s[8:9]
	v_add_f32_e32 v72, v76, v72
	v_fmac_f32_e32 v71, v131, v72
	v_cndmask_b32_e64 v72, 0, v79, s[8:9]
	v_add_f32_e32 v72, v77, v72
	v_fmac_f32_e32 v71, v132, v72
	v_cndmask_b32_e64 v72, 0, v82, s[8:9]
	v_add_f32_e32 v72, v80, v72
	v_fmac_f32_e32 v71, v133, v72
	v_cndmask_b32_e64 v72, 0, v83, s[8:9]
	v_add_f32_e32 v72, v81, v72
	v_cndmask_b32_e64 v69, 0, v69, s[8:9]
	v_fmac_f32_e32 v71, v146, v72
	v_add_f32_e32 v68, v68, v69
	v_fmac_f32_e32 v71, v148, v68
	v_cndmask_b32_e64 v68, v187, v71, s[6:7]
	v_cndmask_b32_e64 v68, v68, v188, s[10:11]
	ds_bpermute_b32 v73, v67, v68
	ds_bpermute_b32 v72, v84, v68
	ds_bpermute_b32 v75, v85, v68
	ds_bpermute_b32 v74, v86, v68
	ds_bpermute_b32 v77, v87, v68
	ds_bpermute_b32 v76, v88, v68
	ds_bpermute_b32 v79, v89, v68
	ds_bpermute_b32 v78, v90, v68
	ds_bpermute_b32 v81, v91, v68
	ds_bpermute_b32 v80, v92, v68
	ds_bpermute_b32 v83, v93, v68
	ds_bpermute_b32 v82, v94, v68
	ds_bpermute_b32 v85, v149, v68
	ds_bpermute_b32 v84, v150, v68
	ds_bpermute_b32 v87, v152, v68
	ds_bpermute_b32 v86, v153, v68
	s_waitcnt lgkmcnt(0)
	v_mov_b32_e32 v69, 1
	v_cmp_lt_f32_e64 s[8:9], v68, v73
	v_cmp_eq_f32_e64 s[10:11], v68, v73
	v_cmp_ne_u32_e64 s[12:13], 0, v143
	s_and_b64 s[10:11], s[10:11], s[12:13]
	s_or_b64 s[8:9], s[8:9], s[10:11]
	v_cndmask_b32_e64 v71, 0, 1, s[8:9]
	v_cmp_lt_f32_e64 s[8:9], v68, v72
	v_cmp_eq_f32_e64 s[10:11], v68, v72
	v_cmp_lt_u32_e64 s[12:13], 1, v143
	s_and_b64 s[10:11], s[10:11], s[12:13]
	s_or_b64 s[8:9], s[8:9], s[10:11]
	v_cndmask_b32_e64 v69, 0, 1, s[8:9]
	v_mov_b32_e32 v72, 1
	v_cmp_lt_f32_e64 s[8:9], v68, v75
	v_cmp_eq_f32_e64 s[10:11], v68, v75
	v_cmp_lt_u32_e64 s[12:13], 2, v143
	s_and_b64 s[10:11], s[10:11], s[12:13]
	s_or_b64 s[8:9], s[8:9], s[10:11]
	v_cndmask_b32_e64 v73, 0, 1, s[8:9]
	v_cmp_lt_f32_e64 s[8:9], v68, v74
	v_cmp_eq_f32_e64 s[10:11], v68, v74
	v_cmp_lt_u32_e64 s[12:13], 3, v143
	s_and_b64 s[10:11], s[10:11], s[12:13]
	s_or_b64 s[8:9], s[8:9], s[10:11]
	v_cndmask_b32_e64 v72, 0, 1, s[8:9]
	v_mov_b32_e32 v74, 1
	v_cmp_lt_f32_e64 s[8:9], v68, v77
	v_cmp_eq_f32_e64 s[10:11], v68, v77
	v_cmp_lt_u32_e64 s[12:13], 4, v143
	s_and_b64 s[10:11], s[10:11], s[12:13]
	s_or_b64 s[8:9], s[8:9], s[10:11]
	v_cndmask_b32_e64 v75, 0, 1, s[8:9]
	v_cmp_lt_f32_e64 s[8:9], v68, v76
	v_cmp_eq_f32_e64 s[10:11], v68, v76
	v_cmp_lt_u32_e64 s[12:13], 5, v143
	s_and_b64 s[10:11], s[10:11], s[12:13]
	s_or_b64 s[8:9], s[8:9], s[10:11]
	v_cndmask_b32_e64 v74, 0, 1, s[8:9]
	v_mov_b32_e32 v76, 1
	v_cmp_lt_f32_e64 s[8:9], v68, v79
	v_cmp_eq_f32_e64 s[10:11], v68, v79
	v_cmp_lt_u32_e64 s[12:13], 6, v143
	s_and_b64 s[10:11], s[10:11], s[12:13]
	s_or_b64 s[8:9], s[8:9], s[10:11]
	v_cndmask_b32_e64 v77, 0, 1, s[8:9]
	v_cmp_lt_f32_e64 s[8:9], v68, v78
	v_cmp_eq_f32_e64 s[10:11], v68, v78
	v_cmp_lt_u32_e64 s[12:13], 7, v143
	s_and_b64 s[10:11], s[10:11], s[12:13]
	s_or_b64 s[8:9], s[8:9], s[10:11]
	v_cndmask_b32_e64 v76, 0, 1, s[8:9]
	v_mov_b32_e32 v78, 1
	v_cmp_lt_f32_e64 s[8:9], v68, v81
	v_cmp_eq_f32_e64 s[10:11], v68, v81
	v_cmp_lt_u32_e64 s[12:13], 8, v143
	s_and_b64 s[10:11], s[10:11], s[12:13]
	s_or_b64 s[8:9], s[8:9], s[10:11]
	v_cndmask_b32_e64 v79, 0, 1, s[8:9]
	v_cmp_lt_f32_e64 s[8:9], v68, v80
	v_cmp_eq_f32_e64 s[10:11], v68, v80
	v_cmp_lt_u32_e64 s[12:13], 9, v143
	s_and_b64 s[10:11], s[10:11], s[12:13]
	s_or_b64 s[8:9], s[8:9], s[10:11]
	v_cndmask_b32_e64 v78, 0, 1, s[8:9]
	v_mov_b32_e32 v80, 1
	v_cmp_lt_f32_e64 s[8:9], v68, v83
	v_cmp_eq_f32_e64 s[10:11], v68, v83
	v_cmp_lt_u32_e64 s[12:13], 10, v143
	s_and_b64 s[10:11], s[10:11], s[12:13]
	s_or_b64 s[8:9], s[8:9], s[10:11]
	v_cndmask_b32_e64 v81, 0, 1, s[8:9]
	v_cmp_lt_f32_e64 s[8:9], v68, v82
	v_cmp_eq_f32_e64 s[10:11], v68, v82
	v_cmp_lt_u32_e64 s[12:13], 11, v143
	s_and_b64 s[10:11], s[10:11], s[12:13]
	s_or_b64 s[8:9], s[8:9], s[10:11]
	v_cndmask_b32_e64 v80, 0, 1, s[8:9]
	v_mov_b32_e32 v82, 1
	v_cmp_lt_f32_e64 s[8:9], v68, v85
	v_cmp_eq_f32_e64 s[10:11], v68, v85
	v_cmp_lt_u32_e64 s[12:13], 12, v143
	s_and_b64 s[10:11], s[10:11], s[12:13]
	s_or_b64 s[8:9], s[8:9], s[10:11]
	v_cndmask_b32_e64 v83, 0, 1, s[8:9]
	v_cmp_lt_f32_e64 s[8:9], v68, v84
	v_cmp_eq_f32_e64 s[10:11], v68, v84
	v_cmp_lt_u32_e64 s[12:13], 13, v143
	s_and_b64 s[10:11], s[10:11], s[12:13]
	s_or_b64 s[8:9], s[8:9], s[10:11]
	v_cndmask_b32_e64 v82, 0, 1, s[8:9]
	v_mov_b32_e32 v84, 1
	v_cmp_lt_f32_e64 s[8:9], v68, v87
	v_cmp_eq_f32_e64 s[10:11], v68, v87
	v_cmp_lt_u32_e64 s[12:13], 14, v143
	s_and_b64 s[10:11], s[10:11], s[12:13]
	s_or_b64 s[8:9], s[8:9], s[10:11]
	v_cndmask_b32_e64 v85, 0, 1, s[8:9]
	v_cmp_lt_f32_e64 s[8:9], v68, v86
	v_cmp_eq_f32_e64 s[10:11], v68, v86
	v_cmp_lt_u32_e64 s[12:13], 15, v143
	s_and_b64 s[10:11], s[10:11], s[12:13]
	s_or_b64 s[8:9], s[8:9], s[10:11]
	v_cndmask_b32_e64 v84, 0, 1, s[8:9]
	v_or_b32_e32 v86, 64, v67
	v_or_b32_e32 v87, 0x44, v67
	v_or_b32_e32 v88, 0x48, v67
	v_or_b32_e32 v89, 0x4c, v67
	v_or_b32_e32 v92, 0x50, v67
	v_or_b32_e32 v93, 0x54, v67
	v_or_b32_e32 v96, 0x58, v67
	v_or_b32_e32 v97, 0x5c, v67
	v_or_b32_e32 v132, 0x60, v67
	v_or_b32_e32 v148, 0x64, v67
	v_or_b32_e32 v149, 0x68, v67
	v_or_b32_e32 v150, 0x6c, v67
	v_or_b32_e32 v152, 0x70, v67
	v_or_b32_e32 v153, 0x74, v67
	v_or_b32_e32 v154, 0x78, v67
	v_or_b32_e32 v67, 0x7c, v67
	ds_bpermute_b32 v91, v86, v68
	ds_bpermute_b32 v90, v87, v68
	ds_bpermute_b32 v95, v88, v68
	ds_bpermute_b32 v94, v89, v68
	ds_bpermute_b32 v131, v92, v68
	ds_bpermute_b32 v130, v93, v68
	ds_bpermute_b32 v146, v96, v68
	ds_bpermute_b32 v133, v97, v68
	ds_bpermute_b32 v132, v132, v68
	ds_bpermute_b32 v97, v148, v68
	ds_bpermute_b32 v96, v149, v68
	ds_bpermute_b32 v93, v150, v68
	ds_bpermute_b32 v92, v152, v68
	ds_bpermute_b32 v89, v153, v68
	ds_bpermute_b32 v88, v154, v68
	ds_bpermute_b32 v67, v67, v68
	s_waitcnt lgkmcnt(0)
	v_mov_b32_e32 v86, 1
	v_cmp_lt_f32_e64 s[8:9], v68, v91
	v_cmp_eq_f32_e64 s[10:11], v68, v91
	v_cmp_lt_u32_e64 s[12:13], 16, v143
	s_and_b64 s[10:11], s[10:11], s[12:13]
	s_or_b64 s[8:9], s[8:9], s[10:11]
	v_cndmask_b32_e64 v87, 0, 1, s[8:9]
	v_cmp_lt_f32_e64 s[8:9], v68, v90
	v_cmp_eq_f32_e64 s[10:11], v68, v90
	v_cmp_lt_u32_e64 s[12:13], 17, v143
	s_and_b64 s[10:11], s[10:11], s[12:13]
	s_or_b64 s[8:9], s[8:9], s[10:11]
	v_cndmask_b32_e64 v86, 0, 1, s[8:9]
	v_mov_b32_e32 v90, 1
	v_cmp_lt_f32_e64 s[8:9], v68, v95
	v_cmp_eq_f32_e64 s[10:11], v68, v95
	v_cmp_lt_u32_e64 s[12:13], 18, v143
	s_and_b64 s[10:11], s[10:11], s[12:13]
	s_or_b64 s[8:9], s[8:9], s[10:11]
	v_cndmask_b32_e64 v91, 0, 1, s[8:9]
	v_cmp_lt_f32_e64 s[8:9], v68, v94
	v_cmp_eq_f32_e64 s[10:11], v68, v94
	v_cmp_lt_u32_e64 s[12:13], 19, v143
	s_and_b64 s[10:11], s[10:11], s[12:13]
	s_or_b64 s[8:9], s[8:9], s[10:11]
	v_cndmask_b32_e64 v90, 0, 1, s[8:9]
	v_mov_b32_e32 v94, 1
	v_cmp_lt_f32_e64 s[8:9], v68, v131
	v_cmp_eq_f32_e64 s[10:11], v68, v131
	v_cmp_lt_u32_e64 s[12:13], 20, v143
	s_and_b64 s[10:11], s[10:11], s[12:13]
	s_or_b64 s[8:9], s[8:9], s[10:11]
	v_cndmask_b32_e64 v95, 0, 1, s[8:9]
	v_cmp_lt_f32_e64 s[8:9], v68, v130
	v_cmp_eq_f32_e64 s[10:11], v68, v130
	v_cmp_lt_u32_e64 s[12:13], 21, v143
	s_and_b64 s[10:11], s[10:11], s[12:13]
	s_or_b64 s[8:9], s[8:9], s[10:11]
	v_cndmask_b32_e64 v94, 0, 1, s[8:9]
	v_mov_b32_e32 v130, 1
	v_cmp_lt_f32_e64 s[8:9], v68, v146
	v_cmp_eq_f32_e64 s[10:11], v68, v146
	v_cmp_lt_u32_e64 s[12:13], 22, v143
	s_and_b64 s[10:11], s[10:11], s[12:13]
	s_or_b64 s[8:9], s[8:9], s[10:11]
	v_cndmask_b32_e64 v131, 0, 1, s[8:9]
	v_cmp_lt_f32_e64 s[8:9], v68, v133
	v_cmp_eq_f32_e64 s[10:11], v68, v133
	v_cmp_lt_u32_e64 s[12:13], 23, v143
	s_and_b64 s[10:11], s[10:11], s[12:13]
	s_or_b64 s[8:9], s[8:9], s[10:11]
	v_cndmask_b32_e64 v130, 0, 1, s[8:9]
	v_mov_b32_e32 v133, 1
	v_cmp_lt_f32_e64 s[8:9], v68, v132
	v_cmp_eq_f32_e64 s[10:11], v68, v132
	v_cmp_lt_u32_e64 s[12:13], 24, v143
	s_and_b64 s[10:11], s[10:11], s[12:13]
	s_or_b64 s[8:9], s[8:9], s[10:11]
	v_cndmask_b32_e64 v146, 0, 1, s[8:9]
	v_cmp_lt_f32_e64 s[8:9], v68, v97
	v_cmp_eq_f32_e64 s[10:11], v68, v97
	v_cmp_lt_u32_e64 s[12:13], 25, v143
	s_and_b64 s[10:11], s[10:11], s[12:13]
	s_or_b64 s[8:9], s[8:9], s[10:11]
	v_cndmask_b32_e64 v133, 0, 1, s[8:9]
	v_mov_b32_e32 v97, 1
	v_cmp_lt_f32_e64 s[8:9], v68, v96
	v_cmp_eq_f32_e64 s[10:11], v68, v96
	v_cmp_lt_u32_e64 s[12:13], 26, v143
	s_and_b64 s[10:11], s[10:11], s[12:13]
	s_or_b64 s[8:9], s[8:9], s[10:11]
	v_cndmask_b32_e64 v132, 0, 1, s[8:9]
	v_cmp_lt_f32_e64 s[8:9], v68, v93
	v_cmp_eq_f32_e64 s[10:11], v68, v93
	v_cmp_lt_u32_e64 s[12:13], 27, v143
	s_and_b64 s[10:11], s[10:11], s[12:13]
	s_or_b64 s[8:9], s[8:9], s[10:11]
	v_cndmask_b32_e64 v97, 0, 1, s[8:9]
	v_mov_b32_e32 v93, 1
	v_cmp_lt_f32_e64 s[8:9], v68, v92
	v_cmp_eq_f32_e64 s[10:11], v68, v92
	v_cmp_lt_u32_e64 s[12:13], 28, v143
	s_and_b64 s[10:11], s[10:11], s[12:13]
	s_or_b64 s[8:9], s[8:9], s[10:11]
	v_cndmask_b32_e64 v96, 0, 1, s[8:9]
	v_cmp_lt_f32_e64 s[8:9], v68, v89
	v_cmp_eq_f32_e64 s[10:11], v68, v89
	v_cmp_lt_u32_e64 s[12:13], 29, v143
	s_and_b64 s[10:11], s[10:11], s[12:13]
	s_or_b64 s[8:9], s[8:9], s[10:11]
	v_cndmask_b32_e64 v93, 0, 1, s[8:9]
	v_cmp_lt_f32_e64 s[8:9], v68, v88
	v_cmp_eq_f32_e64 s[10:11], v68, v88
	v_cmp_eq_u32_e64 s[12:13], 31, v143
	s_and_b64 s[10:11], s[10:11], s[12:13]
	s_or_b64 s[8:9], s[8:9], s[10:11]
	v_cndmask_b32_e64 v89, 0, 1, s[8:9]
	v_add3_u32 v69, v69, v71, v73
	v_add3_u32 v69, v69, v72, v75
	v_add3_u32 v69, v69, v74, v77
	v_add3_u32 v69, v69, v76, v79
	v_add3_u32 v69, v69, v78, v81
	v_add3_u32 v69, v69, v80, v83
	v_add3_u32 v69, v69, v82, v85
	v_cmp_lt_f32_e64 s[8:9], v68, v67
	s_nop 1
	v_addc_co_u32_e64 v67, s[8:9], v69, v84, s[8:9]
	v_add_u32_e32 v67, v67, v87
	v_add3_u32 v67, v67, v86, v91
	v_add3_u32 v67, v67, v90, v95
	v_add3_u32 v67, v67, v94, v131
	v_add3_u32 v67, v67, v130, v146
	v_add3_u32 v67, v67, v133, v132
	v_add3_u32 v67, v67, v97, v96
	v_add3_u32 v67, v67, v93, v89
	v_cmp_gt_u32_e64 s[8:9], 16, v67
	s_and_b64 s[6:7], s[8:9], s[6:7]
	v_cndmask_b32_e64 v67, 0, 1, s[6:7]
	v_cmp_ne_u32_e64 s[6:7], 0, v67
	s_and_saveexec_b64 s[8:9], vcc
	s_nop 0
	v_mov_b32_e32 v68, s7
	v_mov_b32_e32 v69, s6
	v_add_u32_e32 v67, 0x24000, v70
	v_cndmask_b32_e64 v68, v68, v69, s[4:5]
	ds_write_b32 v67, v68
	s_or_b64 exec, exec, s[8:9]
